# non-temporal loads/stores for the rolled-cache copy (once-touched 234 MB stream that competes with hidden activations for the Infinity Cache)
# speedup vs baseline: 1.0002x; 1.0002x over previous
.LBB0_1856:
	v_readlane_b32 s0, v248, 25
	v_readlane_b32 s1, v248, 26
	s_nop 1
	v_lshl_add_u64 v[0:1], s[0:1], 0, v[38:39]
	v_readlane_b32 s0, v248, 23
	v_readlane_b32 s1, v248, 24
	v_lshl_add_u64 v[0:1], v[0:1], 0, v[96:97]
	s_nop 0
	v_lshl_add_u64 v[2:3], s[0:1], 0, v[38:39]
	v_lshl_add_u64 v[2:3], v[2:3], 0, v[96:97]
	global_store_dwordx4 v[2:3], v[20:23], off nt
	global_store_dwordx4 v[0:1], v[28:31], off nt

; DI void cache_copy_part(const Params& P, int part, int rank, int nranks) {
;     ...
;     CP4((size_t)2 * 32 * 2048, (size_t)2048, P.in[2], P.in[3], P.out + O_KWS, P.out + O_VWS, (size_t)16384, (size_t)8192);
;     CP4((size_t)2 * 32 * 57344, (size_t)57344, P.in[4], P.in[5], P.out + O_KBS, P.out + O_VBS, (size_t)262144, (size_t)32768);
.LBB0_1860:
	v_alignbit_b32 v26, v33, v32, 13
	s_mov_b32 s0, 0x92492493
	v_mul_hi_u32 v96, v26, s0
	v_lshrrev_b32_e32 v28, 13, v33
	v_mad_u64_u32 v[24:25], s[0:1], v28, s0, v[96:97]
	v_mov_b32_e32 v96, v24
	s_mov_b32 s2, 0x24924924
	v_mad_u64_u32 v[26:27], s[0:1], v26, s2, v[96:97]
	v_mov_b32_e32 v96, v27
	v_mov_b32_e32 v24, v25
	v_mov_b32_e32 v25, v97
	v_lshl_add_u64 v[24:25], v[24:25], 0, v[96:97]
	v_mad_u64_u32 v[24:25], s[0:1], v28, s2, v[24:25]
	v_lshlrev_b64 v[52:53], 17, v[24:25]
	v_lshl_add_u64 v[24:25], v[52:53], 0, s[18:19]
	s_mov_b64 s[0:1], 0x20000
	v_lshl_add_u64 v[24:25], v[24:25], 0, s[0:1]
	v_lshl_add_u64 v[26:27], v[36:37], 0, v[24:25]
	v_lshl_add_u64 v[24:25], v[38:39], 0, v[24:25]
	global_load_dwordx4 v[28:31], v[26:27], off nt
	s_mov_b64 s[0:1], 0xa000
	global_load_dwordx4 v[24:27], v[24:25], off nt
	v_lshl_add_u64 v[48:49], v[32:33], 0, s[0:1]
	v_cmp_gt_u64_e64 s[38:39], s[12:13], v[48:49]
	s_and_saveexec_b64 s[20:21], s[38:39]
	s_cbranch_execz .LBB0_1862
	v_alignbit_b32 v14, v45, v44, 13
	s_mov_b32 s0, 0x92492493
	v_mul_hi_u32 v96, v14, s0
	v_lshrrev_b32_e32 v20, 13, v45
	v_mad_u64_u32 v[12:13], s[0:1], v20, s0, v[96:97]
	v_mov_b32_e32 v96, v12
	v_mad_u64_u32 v[14:15], s[0:1], v14, s2, v[96:97]
	v_mov_b32_e32 v96, v15
	v_mov_b32_e32 v12, v13
	v_mov_b32_e32 v13, v97
	v_lshl_add_u64 v[12:13], v[12:13], 0, v[96:97]
	v_mad_u64_u32 v[12:13], s[0:1], v20, s2, v[12:13]
	v_readlane_b32 s0, v246, 7
	v_lshlrev_b64 v[12:13], 17, v[12:13]
	v_readlane_b32 s1, v246, 8
	s_nop 1
	v_lshl_add_u64 v[14:15], s[0:1], 0, v[12:13]
	v_readlane_b32 s0, v246, 9
	v_readlane_b32 s1, v246, 10
	s_nop 1
	v_lshl_add_u64 v[20:21], s[0:1], 0, v[12:13]
	v_lshl_add_u64 v[12:13], v[14:15], 0, v[34:35]
	v_lshl_add_u64 v[20:21], v[20:21], 0, v[34:35]
	v_lshl_add_u64 v[12:13], v[12:13], 0, s[18:19]
	v_lshl_add_u64 v[20:21], v[20:21], 0, s[18:19]
	global_load_dwordx4 v[12:15], v[12:13], off nt
	s_nop 0
	global_load_dwordx4 v[20:23], v[20:21], off nt
.LBB0_1862:
	s_or_b64 exec, exec, s[20:21]
	s_mov_b64 s[0:1], 0x14000
	v_lshl_add_u64 v[50:51], v[32:33], 0, s[0:1]
	v_cmp_gt_u64_e64 s[40:41], s[12:13], v[50:51]
	s_and_saveexec_b64 s[20:21], s[40:41]
	s_cbranch_execz .LBB0_1864
	v_alignbit_b32 v6, v43, v42, 13
	s_mov_b32 s0, 0x92492493
	v_mul_hi_u32 v96, v6, s0
	v_lshrrev_b32_e32 v16, 13, v43
	v_mad_u64_u32 v[4:5], s[0:1], v16, s0, v[96:97]
	v_mov_b32_e32 v96, v4
	v_mad_u64_u32 v[6:7], s[0:1], v6, s2, v[96:97]
	v_mov_b32_e32 v96, v7
	v_mov_b32_e32 v4, v5
	v_mov_b32_e32 v5, v97
	v_lshl_add_u64 v[4:5], v[4:5], 0, v[96:97]
	v_mad_u64_u32 v[4:5], s[0:1], v16, s2, v[4:5]
	v_lshlrev_b64 v[4:5], 17, v[4:5]
	v_lshl_add_u64 v[4:5], v[4:5], 0, s[18:19]
	s_mov_b64 s[0:1], 0x160000
	v_lshl_add_u64 v[16:17], v[4:5], 0, s[0:1]
	v_lshl_add_u64 v[4:5], v[36:37], 0, v[16:17]
	v_lshl_add_u64 v[16:17], v[38:39], 0, v[16:17]
	global_load_dwordx4 v[4:7], v[4:5], off nt
	s_nop 0
	global_load_dwordx4 v[16:19], v[16:17], off nt
.LBB0_1864:
	s_or_b64 exec, exec, s[20:21]
	s_mov_b64 s[0:1], 0x1e000
	v_lshl_add_u64 v[46:47], v[32:33], 0, s[0:1]
	v_cmp_gt_u64_e64 s[42:43], s[12:13], v[46:47]
	s_and_saveexec_b64 s[20:21], s[42:43]
	s_cbranch_execz .LBB0_1866
	v_alignbit_b32 v2, v41, v40, 13
	s_mov_b32 s0, 0x92492493
	v_mul_hi_u32 v96, v2, s0
	v_lshrrev_b32_e32 v8, 13, v41
	v_mad_u64_u32 v[0:1], s[0:1], v8, s0, v[96:97]
	v_mov_b32_e32 v96, v0
	v_mad_u64_u32 v[2:3], s[0:1], v2, s2, v[96:97]
	v_mov_b32_e32 v96, v3
	v_mov_b32_e32 v0, v1
	v_mov_b32_e32 v1, v97
	v_lshl_add_u64 v[0:1], v[0:1], 0, v[96:97]
	v_mad_u64_u32 v[0:1], s[0:1], v8, s2, v[0:1]
	v_lshlrev_b64 v[0:1], 17, v[0:1]
	v_lshl_add_u64 v[0:1], v[0:1], 0, s[18:19]
	s_mov_b64 s[0:1], 0x200000
	v_lshl_add_u64 v[8:9], v[0:1], 0, s[0:1]
	v_lshl_add_u64 v[0:1], v[36:37], 0, v[8:9]
	v_lshl_add_u64 v[8:9], v[38:39], 0, v[8:9]
	global_load_dwordx4 v[0:3], v[0:1], off nt
	s_nop 0
	global_load_dwordx4 v[8:11], v[8:9], off nt
.LBB0_1866:
	s_or_b64 exec, exec, s[20:21]
	v_lshl_add_u64 v[52:53], s[90:91], 0, v[52:53]
	v_lshl_add_u64 v[52:53], v[52:53], 0, v[34:35]
	v_lshl_add_u64 v[52:53], v[52:53], 0, s[18:19]
	v_add_co_u32_e32 v54, vcc, 0xa100000, v52
	s_nop 1
	v_addc_co_u32_e32 v55, vcc, 0, v53, vcc
	s_waitcnt vmcnt(0)
	global_store_dwordx4 v[54:55], v[28:31], off nt
	s_nop 1
	v_add_co_u32_e32 v28, vcc, 0xe100000, v52
	s_nop 1
	v_addc_co_u32_e32 v29, vcc, 0, v53, vcc
	global_store_dwordx4 v[28:29], v[24:27], off nt
	s_and_saveexec_b64 s[20:21], s[38:39]
	s_cbranch_execz .LBB0_1869
	v_alignbit_b32 v26, v49, v48, 13
	s_mov_b32 s0, 0x92492493
	v_mul_hi_u32 v96, v26, s0
	v_lshrrev_b32_e32 v28, 13, v49
	v_mad_u64_u32 v[24:25], s[0:1], v28, s0, v[96:97]
	v_mov_b32_e32 v96, v24
	v_mad_u64_u32 v[26:27], s[0:1], v26, s2, v[96:97]
	v_mov_b32_e32 v96, v27
	v_mov_b32_e32 v24, v25
	v_mov_b32_e32 v25, v97
	v_lshl_add_u64 v[24:25], v[24:25], 0, v[96:97]
	v_mad_u64_u32 v[24:25], s[0:1], v28, s2, v[24:25]
	s_mov_b32 s2, 0xe000
	v_mad_u64_u32 v[26:27], s[0:1], v24, s2, 0
	v_mov_b32_e32 v28, v27
	v_mad_u64_u32 v[28:29], s[0:1], v25, s2, v[28:29]
	v_readlane_b32 s0, v248, 27
	v_sub_co_u32_e32 v26, vcc, v48, v26
	v_lshlrev_b64 v[24:25], 20, v[24:25]
	v_readlane_b32 s1, v248, 28
	v_subb_co_u32_e32 v27, vcc, v49, v28, vcc
	s_nop 0
	v_lshl_add_u64 v[28:29], s[0:1], 0, v[24:25]
	v_readlane_b32 s0, v248, 29
	v_readlane_b32 s1, v248, 30
	v_lshlrev_b64 v[26:27], 4, v[26:27]
	v_lshl_add_u64 v[28:29], v[28:29], 0, v[26:27]
	v_lshl_add_u64 v[24:25], s[0:1], 0, v[24:25]
	v_lshl_add_u64 v[24:25], v[24:25], 0, v[26:27]
	global_store_dwordx4 v[28:29], v[12:15], off nt
	global_store_dwordx4 v[24:25], v[20:23], off nt
	s_or_b64 exec, exec, s[20:21]
	s_and_saveexec_b64 s[20:21], s[40:41]
	s_cbranch_execnz .LBB0_1870

; DI void cache_copy_part(const Params& P, int part, int rank, int nranks) {
;     ...
;     CP4((size_t)2 * 32 * 2048, (size_t)2048, P.in[2], P.in[3], P.out + O_KWS, P.out + O_VWS, (size_t)16384, (size_t)8192);
;     CP4((size_t)2 * 32 * 57344, (size_t)57344, P.in[4], P.in[5], P.out + O_KBS, P.out + O_VBS, (size_t)262144, (size_t)32768);
.LBB0_1870:
	v_alignbit_b32 v26, v51, v50, 13
	s_mov_b32 s0, 0x92492493
	v_mul_hi_u32 v96, v26, s0
	v_lshrrev_b32_e32 v28, 13, v51
	v_mad_u64_u32 v[24:25], s[0:1], v28, s0, v[96:97]
	v_mov_b32_e32 v96, v24
	s_mov_b32 s2, 0x24924924
	v_mad_u64_u32 v[26:27], s[0:1], v26, s2, v[96:97]
	v_mov_b32_e32 v96, v27
	v_mov_b32_e32 v24, v25
	v_mov_b32_e32 v25, v97
	v_lshl_add_u64 v[24:25], v[24:25], 0, v[96:97]
	v_mad_u64_u32 v[24:25], s[0:1], v28, s2, v[24:25]
	s_mov_b32 s2, 0xe000
	v_mad_u64_u32 v[26:27], s[0:1], v24, s2, 0
	v_mov_b32_e32 v28, v27
	v_mad_u64_u32 v[28:29], s[0:1], v25, s2, v[28:29]
	v_readlane_b32 s0, v248, 27
	v_sub_co_u32_e32 v26, vcc, v50, v26
	v_lshlrev_b64 v[24:25], 20, v[24:25]
	v_readlane_b32 s1, v248, 28
	v_subb_co_u32_e32 v27, vcc, v51, v28, vcc
	s_nop 0
	v_lshl_add_u64 v[28:29], s[0:1], 0, v[24:25]
	v_readlane_b32 s0, v248, 29
	v_readlane_b32 s1, v248, 30
	v_lshlrev_b64 v[26:27], 4, v[26:27]
	v_lshl_add_u64 v[28:29], v[28:29], 0, v[26:27]
	v_lshl_add_u64 v[24:25], s[0:1], 0, v[24:25]
	v_lshl_add_u64 v[24:25], v[24:25], 0, v[26:27]
	global_store_dwordx4 v[28:29], v[4:7], off nt
	global_store_dwordx4 v[24:25], v[16:19], off nt
	s_or_b64 exec, exec, s[20:21]
	s_and_saveexec_b64 s[20:21], s[42:43]
	s_cbranch_execz .LBB0_1859
.LBB0_1871:
	v_alignbit_b32 v26, v47, v46, 13
	s_mov_b32 s0, 0x92492493
	v_mul_hi_u32 v96, v26, s0
	v_lshrrev_b32_e32 v28, 13, v47
	v_mad_u64_u32 v[24:25], s[0:1], v28, s0, v[96:97]
	v_mov_b32_e32 v96, v24
	s_mov_b32 s2, 0x24924924
	v_mad_u64_u32 v[26:27], s[0:1], v26, s2, v[96:97]
	v_mov_b32_e32 v96, v27
	v_mov_b32_e32 v24, v25
	v_mov_b32_e32 v25, v97
	v_lshl_add_u64 v[24:25], v[24:25], 0, v[96:97]
	v_mad_u64_u32 v[24:25], s[0:1], v28, s2, v[24:25]
	s_mov_b32 s2, 0xe000
	v_mad_u64_u32 v[26:27], s[0:1], v24, s2, 0
	v_mov_b32_e32 v28, v27
	v_mad_u64_u32 v[28:29], s[0:1], v25, s2, v[28:29]
	v_readlane_b32 s0, v248, 27
	v_sub_co_u32_e32 v26, vcc, v46, v26
	v_lshlrev_b64 v[24:25], 20, v[24:25]
	v_readlane_b32 s1, v248, 28
	v_subb_co_u32_e32 v27, vcc, v47, v28, vcc
	s_nop 0
	v_lshl_add_u64 v[28:29], s[0:1], 0, v[24:25]
	v_readlane_b32 s0, v248, 29
	v_readlane_b32 s1, v248, 30
	v_lshlrev_b64 v[26:27], 4, v[26:27]
	v_lshl_add_u64 v[28:29], v[28:29], 0, v[26:27]
	v_lshl_add_u64 v[24:25], s[0:1], 0, v[24:25]
	v_lshl_add_u64 v[24:25], v[24:25], 0, v[26:27]
	global_store_dwordx4 v[28:29], v[0:3], off nt
	global_store_dwordx4 v[24:25], v[8:11], off nt
	s_branch .LBB0_1859

.LBB0_1888:
	v_readlane_b32 s0, v248, 25
	v_readlane_b32 s1, v248, 26
	s_nop 1
	v_lshl_add_u64 v[0:1], s[0:1], 0, v[40:41]
	v_readlane_b32 s0, v248, 23
	v_readlane_b32 s1, v248, 24
	v_lshl_add_u64 v[0:1], v[0:1], 0, v[96:97]
	s_nop 0
	v_lshl_add_u64 v[2:3], s[0:1], 0, v[40:41]
	v_lshl_add_u64 v[2:3], v[2:3], 0, v[96:97]
	global_store_dwordx4 v[2:3], v[16:19], off nt
	global_store_dwordx4 v[0:1], v[24:27], off nt
	s_or_b64 exec, exec, s[16:17]
	s_and_saveexec_b64 s[0:1], s[42:43]
	s_xor_b64 s[0:1], exec, s[0:1]
	s_cbranch_execnz .LBB0_1856
	s_branch .LBB0_1857
